# P5 residual x loads sc1 (L1 bypass)
# speedup vs baseline: 1.0035x; 1.0035x over previous
; __device__ __forceinline__ unsigned cvt_pk_bf16_v(float lo, float hi) { const f32x2c v = {lo, hi}; const bf16x2c b = __builtin_convertvector(v, bf16x2c); return __builtin_bit_cast(unsigned, b); }
;     __device__ __forceinline__ void operator()(const f32x4 (&acc)[2][2][4][2], const Unit& u_, int wr, int wc, int fr, int fq) const {
;     ...
;         const int rowb = u.pm * BM + wr * 64 + (l >> 3); const int colb = u.pn * BM + wc * 32 + 4 * (l & 7);
; #pragma unroll
;         for (int ai = 0; ai < 2; ++ai) {
;             f32x4 xr[4][2][2];
; #pragma unroll
;             for (int m = 0; m < 4; ++m)
; #pragma unroll
;                 for (int bj = 0; bj < 2; ++bj)
; #pragma unroll
;                     for (int t = 0; t < 2; ++t) xr[m][bj][t] = *(const f32x4*)(xp + (size_t)(rowb + ai * HALF + m * 16 + 8 * t) * 1024 + colb + bj * HALF);
;             asm volatile("" ::: "memory");
; #pragma unroll
;             for (int m = 0; m < 4; ++m)
; #pragma unroll
;                 for (int bj = 0; bj < 2; ++bj) { f32x4 o[2]; xchg_f32(xl, fr, fq, l, acc[ai][bj][m][0], acc[ai][bj][m][1], o[0], o[1]);
; #pragma unroll
;                     for (int t = 0; t < 2; ++t) { const f32x4 v = o[t] + xr[m][bj][t]; u32x2 w; w.x = cvt_pk_bf16_v(v[0], v[1]); w.y = cvt_pk_bf16_v(v[2], v[3]);
;                         *(u32x2*)(h1b + (size_t)(rowb + ai * HALF + m * 16 + 8 * t) * 1024 + colb + bj * HALF) = w; } }
;             asm volatile("" ::: "memory");
.LBB0_836:
	s_mov_b64 s[56:57], -1
	v_lshl_add_u32 v206, s8, 8, v233
	v_lshl_or_b32 v222, s9, 8, v234
	v_ashrrev_i32_e32 v223, 31, v222
	v_ashrrev_i32_e32 v207, 31, v206
	v_lshl_add_u64 v[204:205], v[222:223], 2, s[68:69]
	v_lshlrev_b64 v[130:131], 12, v[206:207]
	v_or_b32_e32 v220, 8, v206
	v_lshl_add_u64 v[130:131], v[204:205], 0, v[130:131]
	v_ashrrev_i32_e32 v221, 31, v220
	global_load_dwordx4 v[238:241], v[130:131], off sc1
	v_lshlrev_b64 v[132:133], 12, v[220:221]
	v_lshl_add_u64 v[132:133], v[204:205], 0, v[132:133]
	global_load_dwordx4 v[242:245], v[132:133], off sc1
	global_load_dwordx4 v[178:181], v[130:131], off offset:512 sc1
	global_load_dwordx4 v[182:185], v[132:133], off offset:512 sc1
	v_or_b32_e32 v218, 16, v206
	v_ashrrev_i32_e32 v219, 31, v218
	v_lshlrev_b64 v[130:131], 12, v[218:219]
	v_lshl_add_u64 v[130:131], v[204:205], 0, v[130:131]
	global_load_dwordx4 v[174:177], v[130:131], off sc1
	v_or_b32_e32 v216, 24, v206
	v_ashrrev_i32_e32 v217, 31, v216
	v_lshlrev_b64 v[132:133], 12, v[216:217]
	v_lshl_add_u64 v[132:133], v[204:205], 0, v[132:133]
	global_load_dwordx4 v[170:173], v[132:133], off sc1
	global_load_dwordx4 v[166:169], v[130:131], off offset:512 sc1
	global_load_dwordx4 v[162:165], v[132:133], off offset:512 sc1
	v_or_b32_e32 v212, 32, v206
	v_ashrrev_i32_e32 v213, 31, v212
	v_lshlrev_b64 v[130:131], 12, v[212:213]
	v_lshl_add_u64 v[130:131], v[204:205], 0, v[130:131]
	global_load_dwordx4 v[154:157], v[130:131], off sc1
	v_or_b32_e32 v214, 40, v206
	v_ashrrev_i32_e32 v215, 31, v214
	v_lshlrev_b64 v[132:133], 12, v[214:215]
	v_lshl_add_u64 v[132:133], v[204:205], 0, v[132:133]
	global_load_dwordx4 v[158:161], v[132:133], off sc1
	global_load_dwordx4 v[146:149], v[130:131], off offset:512 sc1
	global_load_dwordx4 v[142:145], v[132:133], off offset:512 sc1
	v_or_b32_e32 v208, 48, v206
	v_ashrrev_i32_e32 v209, 31, v208
	v_lshlrev_b64 v[130:131], 12, v[208:209]
	v_lshl_add_u64 v[130:131], v[204:205], 0, v[130:131]
	global_load_dwordx4 v[138:141], v[130:131], off sc1
	v_or_b32_e32 v210, 56, v206
	v_ashrrev_i32_e32 v211, 31, v210
	v_lshlrev_b64 v[132:133], 12, v[210:211]
	v_lshl_add_u64 v[132:133], v[204:205], 0, v[132:133]
	global_load_dwordx4 v[150:153], v[132:133], off sc1
	global_load_dwordx4 v[134:137], v[130:131], off offset:512 sc1
	s_nop 0
	global_load_dwordx4 v[130:133], v[132:133], off offset:512 sc1
	ds_write_b128 v236, v[126:129]
	ds_write_b128 v236, v[122:125] offset:16
	ds_read_b128 v[122:125], v237
	ds_read_b128 v[126:129], v237 offset:1152
	s_cmp_eq_u32 s74, s72
	s_waitcnt vmcnt(0) lgkmcnt(0)
	v_pk_add_f32 v[122:123], v[238:239], v[122:123]
	v_pk_add_f32 v[128:129], v[244:245], v[128:129]
	v_pk_add_f32 v[126:127], v[242:243], v[126:127]
	v_pk_add_f32 v[124:125], v[240:241], v[124:125]
	v_cvt_pk_bf16_f32 v238, v122, v123
	v_lshlrev_b64 v[122:123], 11, v[206:207]
	v_cvt_pk_bf16_f32 v126, v126, v127
	v_cvt_pk_bf16_f32 v127, v128, v129
	v_lshlrev_b64 v[128:129], 11, v[220:221]
	v_cvt_pk_bf16_f32 v239, v124, v125
	v_lshl_add_u64 v[124:125], s[14:15], 0, v[122:123]
	v_lshlrev_b64 v[122:123], 1, v[222:223]
	v_lshl_add_u64 v[128:129], s[14:15], 0, v[128:129]
	v_lshl_add_u64 v[124:125], v[124:125], 0, v[122:123]
	v_lshl_add_u64 v[128:129], v[128:129], 0, v[122:123]
	global_store_dwordx2 v[124:125], v[238:239], off
	global_store_dwordx2 v[128:129], v[126:127], off
	ds_write_b128 v236, v[118:121]
	ds_write_b128 v236, v[114:117] offset:16
	ds_read_b128 v[114:117], v237
	ds_read_b128 v[118:121], v237 offset:1152
	s_waitcnt lgkmcnt(1)
	v_pk_add_f32 v[116:117], v[180:181], v[116:117]
	v_pk_add_f32 v[114:115], v[178:179], v[114:115]
	s_nop 0
	v_cvt_pk_bf16_f32 v114, v114, v115
	v_cvt_pk_bf16_f32 v115, v116, v117
	global_store_dwordx2 v[124:125], v[114:115], off offset:256
	s_waitcnt lgkmcnt(0)
	v_pk_add_f32 v[114:115], v[184:185], v[120:121]
	v_pk_add_f32 v[116:117], v[182:183], v[118:119]
	s_nop 0
	v_cvt_pk_bf16_f32 v116, v116, v117
	v_cvt_pk_bf16_f32 v117, v114, v115
	global_store_dwordx2 v[128:129], v[116:117], off offset:256
	ds_write_b128 v236, v[110:113]
	ds_write_b128 v236, v[106:109] offset:16
	ds_read_b128 v[106:109], v237
	ds_read_b128 v[110:113], v237 offset:1152
	s_waitcnt lgkmcnt(1)
	v_pk_add_f32 v[108:109], v[176:177], v[108:109]
	v_pk_add_f32 v[106:107], v[174:175], v[106:107]
	s_waitcnt lgkmcnt(0)
	v_pk_add_f32 v[110:111], v[170:171], v[110:111]
	v_cvt_pk_bf16_f32 v106, v106, v107
	v_cvt_pk_bf16_f32 v107, v108, v109
	v_lshlrev_b64 v[108:109], 11, v[218:219]
	v_lshl_add_u64 v[108:109], s[14:15], 0, v[108:109]
	v_lshl_add_u64 v[108:109], v[108:109], 0, v[122:123]
	global_store_dwordx2 v[108:109], v[106:107], off
	v_pk_add_f32 v[106:107], v[172:173], v[112:113]
	v_cvt_pk_bf16_f32 v110, v110, v111
	v_cvt_pk_bf16_f32 v111, v106, v107
	v_lshlrev_b64 v[106:107], 11, v[216:217]
	v_lshl_add_u64 v[106:107], s[14:15], 0, v[106:107]
	v_lshl_add_u64 v[106:107], v[106:107], 0, v[122:123]
	global_store_dwordx2 v[106:107], v[110:111], off
	ds_write_b128 v236, v[102:105]
	ds_write_b128 v236, v[98:101] offset:16
	ds_read_b128 v[98:101], v237
	ds_read_b128 v[102:105], v237 offset:1152
	s_waitcnt lgkmcnt(1)
	v_pk_add_f32 v[100:101], v[168:169], v[100:101]
	v_pk_add_f32 v[98:99], v[166:167], v[98:99]
	s_nop 0
	v_cvt_pk_bf16_f32 v98, v98, v99
	v_cvt_pk_bf16_f32 v99, v100, v101
	global_store_dwordx2 v[108:109], v[98:99], off offset:256
	s_waitcnt lgkmcnt(0)
	v_pk_add_f32 v[98:99], v[164:165], v[104:105]
	v_pk_add_f32 v[100:101], v[162:163], v[102:103]
	v_add_u32_e32 v104, 0xa0, v206
	v_cvt_pk_bf16_f32 v100, v100, v101
	v_cvt_pk_bf16_f32 v101, v98, v99
	global_store_dwordx2 v[106:107], v[100:101], off offset:256
	ds_write_b128 v236, v[94:97]
	ds_write_b128 v236, v[90:93] offset:16
	ds_read_b128 v[90:93], v237
	ds_read_b128 v[94:97], v237 offset:1152
	v_ashrrev_i32_e32 v105, 31, v104
	v_add_u32_e32 v102, 0xa8, v206
	v_ashrrev_i32_e32 v103, 31, v102
	s_waitcnt lgkmcnt(1)
; __device__ __forceinline__ unsigned cvt_pk_bf16_v(float lo, float hi) { const f32x2c v = {lo, hi}; const bf16x2c b = __builtin_convertvector(v, bf16x2c); return __builtin_bit_cast(unsigned, b); }
;     __device__ __forceinline__ void operator()(const f32x4 (&acc)[2][2][4][2], const Unit& u_, int wr, int wc, int fr, int fq) const {
;     ...
;         for (int ai = 0; ai < 2; ++ai) {
;             f32x4 xr[4][2][2];
; #pragma unroll
;             for (int m = 0; m < 4; ++m)
; #pragma unroll
;                 for (int bj = 0; bj < 2; ++bj)
; #pragma unroll
;                     for (int t = 0; t < 2; ++t) xr[m][bj][t] = *(const f32x4*)(xp + (size_t)(rowb + ai * HALF + m * 16 + 8 * t) * 1024 + colb + bj * HALF);
;             asm volatile("" ::: "memory");
; #pragma unroll
;             for (int m = 0; m < 4; ++m)
; #pragma unroll
;                 for (int bj = 0; bj < 2; ++bj) { f32x4 o[2]; xchg_f32(xl, fr, fq, l, acc[ai][bj][m][0], acc[ai][bj][m][1], o[0], o[1]);
; #pragma unroll
;                     for (int t = 0; t < 2; ++t) { const f32x4 v = o[t] + xr[m][bj][t]; u32x2 w; w.x = cvt_pk_bf16_v(v[0], v[1]); w.y = cvt_pk_bf16_v(v[2], v[3]);
;                         *(u32x2*)(h1b + (size_t)(rowb + ai * HALF + m * 16 + 8 * t) * 1024 + colb + bj * HALF) = w; } }
	v_pk_add_f32 v[92:93], v[156:157], v[92:93]
	v_pk_add_f32 v[90:91], v[154:155], v[90:91]
	s_waitcnt lgkmcnt(0)
	v_pk_add_f32 v[94:95], v[158:159], v[94:95]
	v_cvt_pk_bf16_f32 v90, v90, v91
	v_cvt_pk_bf16_f32 v91, v92, v93
	v_lshlrev_b64 v[92:93], 11, v[212:213]
	v_lshl_add_u64 v[92:93], s[14:15], 0, v[92:93]
	v_lshl_add_u64 v[92:93], v[92:93], 0, v[122:123]
	global_store_dwordx2 v[92:93], v[90:91], off
	v_pk_add_f32 v[90:91], v[160:161], v[96:97]
	v_cvt_pk_bf16_f32 v94, v94, v95
	v_cvt_pk_bf16_f32 v95, v90, v91
	v_lshlrev_b64 v[90:91], 11, v[214:215]
	v_lshl_add_u64 v[90:91], s[14:15], 0, v[90:91]
	v_lshl_add_u64 v[90:91], v[90:91], 0, v[122:123]
	global_store_dwordx2 v[90:91], v[94:95], off
	ds_write_b128 v236, v[86:89]
	ds_write_b128 v236, v[82:85] offset:16
	ds_read_b128 v[82:85], v237
	ds_read_b128 v[86:89], v237 offset:1152
	v_add_u32_e32 v100, 0xb0, v206
	v_ashrrev_i32_e32 v101, 31, v100
	v_add_u32_e32 v98, 0xb8, v206
	s_waitcnt lgkmcnt(1)
	v_pk_add_f32 v[84:85], v[148:149], v[84:85]
	v_pk_add_f32 v[82:83], v[146:147], v[82:83]
	v_add_u32_e32 v146, 0x98, v206
	v_cvt_pk_bf16_f32 v82, v82, v83
	v_cvt_pk_bf16_f32 v83, v84, v85
	global_store_dwordx2 v[92:93], v[82:83], off offset:256
	s_waitcnt lgkmcnt(0)
	v_pk_add_f32 v[82:83], v[144:145], v[88:89]
	v_pk_add_f32 v[84:85], v[142:143], v[86:87]
	v_add_u32_e32 v142, 0x88, v206
	v_cvt_pk_bf16_f32 v84, v84, v85
	v_cvt_pk_bf16_f32 v85, v82, v83
	global_store_dwordx2 v[90:91], v[84:85], off offset:256
	ds_write_b128 v236, v[78:81]
	ds_write_b128 v236, v[74:77] offset:16
	ds_read_b128 v[74:77], v237
	ds_read_b128 v[78:81], v237 offset:1152
	v_ashrrev_i32_e32 v143, 31, v142
	v_add_u32_e32 v144, 0x90, v206
	v_ashrrev_i32_e32 v145, 31, v144
	s_waitcnt lgkmcnt(1)
	v_pk_add_f32 v[76:77], v[140:141], v[76:77]
	v_pk_add_f32 v[74:75], v[138:139], v[74:75]
	s_waitcnt lgkmcnt(0)
	v_pk_add_f32 v[78:79], v[150:151], v[78:79]
	v_cvt_pk_bf16_f32 v74, v74, v75
	v_cvt_pk_bf16_f32 v75, v76, v77
	v_lshlrev_b64 v[76:77], 11, v[208:209]
	v_lshl_add_u64 v[76:77], s[14:15], 0, v[76:77]
	v_lshl_add_u64 v[76:77], v[76:77], 0, v[122:123]
	global_store_dwordx2 v[76:77], v[74:75], off
	v_pk_add_f32 v[74:75], v[152:153], v[80:81]
	v_cvt_pk_bf16_f32 v78, v78, v79
	v_cvt_pk_bf16_f32 v79, v74, v75
	v_lshlrev_b64 v[74:75], 11, v[210:211]
	v_lshl_add_u64 v[74:75], s[14:15], 0, v[74:75]
	v_lshl_add_u64 v[74:75], v[74:75], 0, v[122:123]
	global_store_dwordx2 v[74:75], v[78:79], off
	ds_write_b128 v236, v[70:73]
	ds_write_b128 v236, v[66:69] offset:16
	ds_read_b128 v[66:69], v237
	ds_read_b128 v[70:73], v237 offset:1152
	v_add_u32_e32 v140, 0x80, v206
	v_ashrrev_i32_e32 v141, 31, v140
	v_ashrrev_i32_e32 v147, 31, v146
	s_waitcnt lgkmcnt(1)
	v_pk_add_f32 v[68:69], v[136:137], v[68:69]
	v_pk_add_f32 v[66:67], v[134:135], v[66:67]
	v_ashrrev_i32_e32 v99, 31, v98
	v_cvt_pk_bf16_f32 v66, v66, v67
	v_cvt_pk_bf16_f32 v67, v68, v69
	global_store_dwordx2 v[76:77], v[66:67], off offset:256
	s_waitcnt lgkmcnt(0)
	v_pk_add_f32 v[66:67], v[132:133], v[72:73]
	v_pk_add_f32 v[68:69], v[130:131], v[70:71]
	s_nop 0
	v_cvt_pk_bf16_f32 v68, v68, v69
	v_cvt_pk_bf16_f32 v69, v66, v67
	global_store_dwordx2 v[74:75], v[68:69], off offset:256
	v_lshlrev_b64 v[66:67], 12, v[140:141]
	v_lshl_add_u64 v[66:67], v[204:205], 0, v[66:67]
	global_load_dwordx4 v[106:109], v[66:67], off sc1
	v_lshlrev_b64 v[68:69], 12, v[142:143]
	v_lshl_add_u64 v[68:69], v[204:205], 0, v[68:69]
	global_load_dwordx4 v[110:113], v[68:69], off sc1
	global_load_dwordx4 v[114:117], v[66:67], off offset:512 sc1
	global_load_dwordx4 v[118:121], v[68:69], off offset:512 sc1
	v_lshlrev_b64 v[66:67], 12, v[144:145]
	v_lshl_add_u64 v[66:67], v[204:205], 0, v[66:67]
	global_load_dwordx4 v[124:127], v[66:67], off sc1
	v_lshlrev_b64 v[68:69], 12, v[146:147]
	v_lshl_add_u64 v[68:69], v[204:205], 0, v[68:69]
	global_load_dwordx4 v[128:131], v[68:69], off sc1
	global_load_dwordx4 v[132:135], v[66:67], off offset:512 sc1
	global_load_dwordx4 v[136:139], v[68:69], off offset:512 sc1
	v_lshlrev_b64 v[66:67], 12, v[104:105]
	v_lshl_add_u64 v[66:67], v[204:205], 0, v[66:67]
	global_load_dwordx4 v[94:97], v[66:67], off sc1
	v_lshlrev_b64 v[68:69], 12, v[102:103]
	v_lshl_add_u64 v[68:69], v[204:205], 0, v[68:69]
	global_load_dwordx4 v[90:93], v[68:69], off sc1
	global_load_dwordx4 v[86:89], v[66:67], off offset:512 sc1
	global_load_dwordx4 v[82:85], v[68:69], off offset:512 sc1
	v_lshlrev_b64 v[66:67], 12, v[100:101]
	v_lshl_add_u64 v[66:67], v[204:205], 0, v[66:67]
	global_load_dwordx4 v[78:81], v[66:67], off sc1
	v_lshlrev_b64 v[68:69], 12, v[98:99]
	v_lshl_add_u64 v[68:69], v[204:205], 0, v[68:69]
	global_load_dwordx4 v[74:77], v[68:69], off sc1
	global_load_dwordx4 v[70:73], v[66:67], off offset:512 sc1
	s_nop 0
	global_load_dwordx4 v[66:69], v[68:69], off offset:512 sc1
	ds_write_b128 v236, v[62:65]
	ds_write_b128 v236, v[58:61] offset:16
	ds_read_b128 v[58:61], v237
	ds_read_b128 v[62:65], v237 offset:1152
	s_waitcnt vmcnt(15) lgkmcnt(1)
	v_pk_add_f32 v[60:61], v[108:109], v[60:61]
	v_pk_add_f32 v[58:59], v[106:107], v[58:59]
	s_waitcnt vmcnt(14) lgkmcnt(0)
	v_pk_add_f32 v[62:63], v[110:111], v[62:63]
	v_cvt_pk_bf16_f32 v58, v58, v59
	v_cvt_pk_bf16_f32 v59, v60, v61
	v_lshlrev_b64 v[60:61], 11, v[140:141]
	v_lshl_add_u64 v[60:61], s[14:15], 0, v[60:61]
	v_lshl_add_u64 v[60:61], v[60:61], 0, v[122:123]
	global_store_dwordx2 v[60:61], v[58:59], off
	v_pk_add_f32 v[58:59], v[112:113], v[64:65]
	v_cvt_pk_bf16_f32 v62, v62, v63
	v_cvt_pk_bf16_f32 v63, v58, v59
	v_lshlrev_b64 v[58:59], 11, v[142:143]
	v_lshl_add_u64 v[58:59], s[14:15], 0, v[58:59]
	v_lshl_add_u64 v[58:59], v[58:59], 0, v[122:123]
	global_store_dwordx2 v[58:59], v[62:63], off
	ds_write_b128 v236, v[54:57]
	ds_write_b128 v236, v[50:53] offset:16
	ds_read_b128 v[50:53], v237
	ds_read_b128 v[54:57], v237 offset:1152
	s_waitcnt vmcnt(15) lgkmcnt(1)
; __device__ __forceinline__ unsigned cvt_pk_bf16_v(float lo, float hi) { const f32x2c v = {lo, hi}; const bf16x2c b = __builtin_convertvector(v, bf16x2c); return __builtin_bit_cast(unsigned, b); }
;     __device__ __forceinline__ void operator()(const f32x4 (&acc)[2][2][4][2], const Unit& u_, int wr, int wc, int fr, int fq) const {
;     ...
; #pragma unroll
;             for (int m = 0; m < 4; ++m)
; #pragma unroll
;                 for (int bj = 0; bj < 2; ++bj) { f32x4 o[2]; xchg_f32(xl, fr, fq, l, acc[ai][bj][m][0], acc[ai][bj][m][1], o[0], o[1]);
; #pragma unroll
;                     for (int t = 0; t < 2; ++t) { const f32x4 v = o[t] + xr[m][bj][t]; u32x2 w; w.x = cvt_pk_bf16_v(v[0], v[1]); w.y = cvt_pk_bf16_v(v[2], v[3]);
;                         *(u32x2*)(h1b + (size_t)(rowb + ai * HALF + m * 16 + 8 * t) * 1024 + colb + bj * HALF) = w; } }
;             asm volatile("" ::: "memory");
	v_pk_add_f32 v[52:53], v[116:117], v[52:53]
	v_pk_add_f32 v[50:51], v[114:115], v[50:51]
	s_nop 0
	v_cvt_pk_bf16_f32 v50, v50, v51
	v_cvt_pk_bf16_f32 v51, v52, v53
	global_store_dwordx2 v[60:61], v[50:51], off offset:256
	s_waitcnt vmcnt(15) lgkmcnt(0)
	v_pk_add_f32 v[50:51], v[120:121], v[56:57]
	v_pk_add_f32 v[52:53], v[118:119], v[54:55]
	s_nop 0
	v_cvt_pk_bf16_f32 v52, v52, v53
	v_cvt_pk_bf16_f32 v53, v50, v51
	global_store_dwordx2 v[58:59], v[52:53], off offset:256
	ds_write_b128 v236, v[46:49]
	ds_write_b128 v236, v[42:45] offset:16
	ds_read_b128 v[42:45], v237
	ds_read_b128 v[46:49], v237 offset:1152
	s_waitcnt vmcnt(15) lgkmcnt(1)
	v_pk_add_f32 v[44:45], v[126:127], v[44:45]
	v_pk_add_f32 v[42:43], v[124:125], v[42:43]
	s_waitcnt vmcnt(14) lgkmcnt(0)
	v_pk_add_f32 v[46:47], v[128:129], v[46:47]
	v_cvt_pk_bf16_f32 v42, v42, v43
	v_cvt_pk_bf16_f32 v43, v44, v45
	v_lshlrev_b64 v[44:45], 11, v[144:145]
	v_lshl_add_u64 v[44:45], s[14:15], 0, v[44:45]
	v_lshl_add_u64 v[44:45], v[44:45], 0, v[122:123]
	global_store_dwordx2 v[44:45], v[42:43], off
	v_pk_add_f32 v[42:43], v[130:131], v[48:49]
	v_cvt_pk_bf16_f32 v46, v46, v47
	v_cvt_pk_bf16_f32 v47, v42, v43
	v_lshlrev_b64 v[42:43], 11, v[146:147]
	v_lshl_add_u64 v[42:43], s[14:15], 0, v[42:43]
	v_lshl_add_u64 v[42:43], v[42:43], 0, v[122:123]
	global_store_dwordx2 v[42:43], v[46:47], off
	ds_write_b128 v236, v[38:41]
	ds_write_b128 v236, v[34:37] offset:16
	ds_read_b128 v[34:37], v237
	ds_read_b128 v[38:41], v237 offset:1152
	s_waitcnt vmcnt(15) lgkmcnt(1)
	v_pk_add_f32 v[36:37], v[134:135], v[36:37]
	v_pk_add_f32 v[34:35], v[132:133], v[34:35]
	s_nop 0
	v_cvt_pk_bf16_f32 v34, v34, v35
	v_cvt_pk_bf16_f32 v35, v36, v37
	global_store_dwordx2 v[44:45], v[34:35], off offset:256
	s_waitcnt vmcnt(15) lgkmcnt(0)
	v_pk_add_f32 v[34:35], v[138:139], v[40:41]
	v_pk_add_f32 v[36:37], v[136:137], v[38:39]
	s_nop 0
	v_cvt_pk_bf16_f32 v36, v36, v37
	v_cvt_pk_bf16_f32 v37, v34, v35
	global_store_dwordx2 v[42:43], v[36:37], off offset:256
	ds_write_b128 v236, v[30:33]
	ds_write_b128 v236, v[26:29] offset:16
	ds_read_b128 v[26:29], v237
	ds_read_b128 v[30:33], v237 offset:1152
	s_waitcnt vmcnt(15) lgkmcnt(1)
	v_pk_add_f32 v[28:29], v[96:97], v[28:29]
	v_pk_add_f32 v[26:27], v[94:95], v[26:27]
	s_waitcnt vmcnt(14) lgkmcnt(0)
	v_pk_add_f32 v[30:31], v[90:91], v[30:31]
	v_cvt_pk_bf16_f32 v26, v26, v27
	v_cvt_pk_bf16_f32 v27, v28, v29
	v_lshlrev_b64 v[28:29], 11, v[104:105]
	v_lshl_add_u64 v[28:29], s[14:15], 0, v[28:29]
	v_lshl_add_u64 v[28:29], v[28:29], 0, v[122:123]
	global_store_dwordx2 v[28:29], v[26:27], off
	v_pk_add_f32 v[26:27], v[92:93], v[32:33]
	v_cvt_pk_bf16_f32 v30, v30, v31
	v_cvt_pk_bf16_f32 v31, v26, v27
	v_lshlrev_b64 v[26:27], 11, v[102:103]
	v_lshl_add_u64 v[26:27], s[14:15], 0, v[26:27]
	v_lshl_add_u64 v[26:27], v[26:27], 0, v[122:123]
	global_store_dwordx2 v[26:27], v[30:31], off
	ds_write_b128 v236, v[22:25]
	ds_write_b128 v236, v[18:21] offset:16
	ds_read_b128 v[18:21], v237
	ds_read_b128 v[22:25], v237 offset:1152
	s_waitcnt vmcnt(15) lgkmcnt(1)
	v_pk_add_f32 v[20:21], v[88:89], v[20:21]
	v_pk_add_f32 v[18:19], v[86:87], v[18:19]
	s_nop 0
	v_cvt_pk_bf16_f32 v18, v18, v19
	v_cvt_pk_bf16_f32 v19, v20, v21
	global_store_dwordx2 v[28:29], v[18:19], off offset:256
	s_waitcnt vmcnt(15) lgkmcnt(0)
	v_pk_add_f32 v[18:19], v[84:85], v[24:25]
	v_pk_add_f32 v[20:21], v[82:83], v[22:23]
	s_nop 0
	v_cvt_pk_bf16_f32 v20, v20, v21
	v_cvt_pk_bf16_f32 v21, v18, v19
	global_store_dwordx2 v[26:27], v[20:21], off offset:256
	ds_write_b128 v236, v[14:17]
	ds_write_b128 v236, v[10:13] offset:16
	ds_read_b128 v[10:13], v237
	ds_read_b128 v[14:17], v237 offset:1152
	s_waitcnt vmcnt(15) lgkmcnt(1)
	v_pk_add_f32 v[12:13], v[80:81], v[12:13]
	v_pk_add_f32 v[10:11], v[78:79], v[10:11]
	s_waitcnt vmcnt(14) lgkmcnt(0)
	v_pk_add_f32 v[14:15], v[74:75], v[14:15]
	v_cvt_pk_bf16_f32 v10, v10, v11
	v_cvt_pk_bf16_f32 v11, v12, v13
	v_lshlrev_b64 v[12:13], 11, v[100:101]
	v_lshl_add_u64 v[12:13], s[14:15], 0, v[12:13]
	v_lshl_add_u64 v[12:13], v[12:13], 0, v[122:123]
	global_store_dwordx2 v[12:13], v[10:11], off
	v_pk_add_f32 v[10:11], v[76:77], v[16:17]
	v_cvt_pk_bf16_f32 v14, v14, v15
	v_cvt_pk_bf16_f32 v15, v10, v11
	v_lshlrev_b64 v[10:11], 11, v[98:99]
	v_lshl_add_u64 v[10:11], s[14:15], 0, v[10:11]
	v_lshl_add_u64 v[10:11], v[10:11], 0, v[122:123]
	global_store_dwordx2 v[10:11], v[14:15], off
	ds_write_b128 v236, v[6:9]
	ds_write_b128 v236, v[2:5] offset:16
	ds_read_b128 v[2:5], v237
	ds_read_b128 v[6:9], v237 offset:1152
	s_waitcnt vmcnt(15) lgkmcnt(1)
	v_pk_add_f32 v[4:5], v[72:73], v[4:5]
	v_pk_add_f32 v[2:3], v[70:71], v[2:3]
	s_nop 0
	v_cvt_pk_bf16_f32 v2, v2, v3
	v_cvt_pk_bf16_f32 v3, v4, v5
	global_store_dwordx2 v[12:13], v[2:3], off offset:256
	s_waitcnt vmcnt(15) lgkmcnt(0)
	v_pk_add_f32 v[2:3], v[68:69], v[8:9]
	v_pk_add_f32 v[4:5], v[66:67], v[6:7]
	s_nop 0
	v_cvt_pk_bf16_f32 v4, v4, v5
	v_cvt_pk_bf16_f32 v5, v2, v3
	global_store_dwordx2 v[10:11], v[4:5], off offset:256
	s_cbranch_scc1 .LBB0_831
	s_andn2_b64 vcc, exec, s[48:49]
	s_cbranch_vccnz .LBB0_830
	s_barrier
	s_branch .LBB0_830
